# up-projection epilogue VALU cut: canonicalising v_max deleted, scalar v_mul pairs packed into v_pk_mul_f32, hazards re-padded (on E1+E3+E25)
# speedup vs baseline: 1.0016x; 1.0011x over previous
.LBB0_1169:
	v_lshl_add_u32 v156, s0, 8, v119
	v_ashrrev_i32_e32 v157, 31, v156
	v_lshl_add_u64 v[156:157], v[156:157], 2, s[26:27]
	global_load_dword v160, v[156:157], off sc1
	s_lshl_b32 s48, s48, 2
	s_ashr_i32 s49, s48, 31
	v_max_f32_e32 v162, 0, v120
	s_ashr_i32 s1, s0, 31
	v_max_f32_e32 v164, 0, v121
	s_or_b64 s[4:5], s[48:49], s[94:95]
	s_lshl_b64 s[0:1], s[0:1], 23
	v_max_f32_e32 v161, 0, v124
	s_lshl_b64 s[4:5], s[4:5], 15
	v_max_f32_e32 v163, 0, v125
	s_add_u32 s0, s69, s0
	s_addc_u32 s1, s70, s1
	s_add_u32 s0, s0, s4
	s_addc_u32 s1, s1, s5
	s_add_u32 s0, s0, s78
	s_addc_u32 s1, s1, 0
	v_max_f32_e32 v132, 0, v132
	v_max_f32_e32 v128, 0, v128
	v_max_f32_e32 v133, 0, v133
	v_max_f32_e32 v129, 0, v129
	v_max_f32_e32 v134, 0, v134
	v_max_f32_e32 v135, 0, v135
	v_max_f32_e32 v126, 0, v126
	v_max_f32_e32 v127, 0, v127
	v_max_f32_e32 v130, 0, v130
	v_max_f32_e32 v131, 0, v131
	v_max_f32_e32 v122, 0, v122
	v_max_f32_e32 v123, 0, v123
	v_max_f32_e32 v100, 0, v100
	v_max_f32_e32 v110, 0, v110
	v_max_f32_e32 v98, 0, v98
	v_max_f32_e32 v103, 0, v103
	v_max_f32_e32 v99, 0, v99
	v_max_f32_e32 v104, 0, v104
	v_max_f32_e32 v101, 0, v101
	v_max_f32_e32 v111, 0, v111
	v_max_f32_e32 v112, 0, v112
	v_max_f32_e32 v108, 0, v108
	v_max_f32_e32 v113, 0, v113
	v_max_f32_e32 v109, 0, v109
	v_max_f32_e32 v102, 0, v102
	s_waitcnt vmcnt(0)
	v_fmamk_f32 v120, v160, 0x39800000, v230
	v_mul_f32_e32 v121, 0x4f800000, v120
	v_cmp_gt_f32_e32 vcc, s28, v120
	s_nop 1
	v_cndmask_b32_e32 v124, v120, v121, vcc
	v_sqrt_f32_e32 v125, v124
	v_lshl_add_u64 v[120:121], s[0:1], 0, v[114:115]
	v_add_u32_e32 v160, -1, v125
	v_add_u32_e32 v165, 1, v125
	v_fma_f32 v166, -v160, v125, v124
	v_fma_f32 v167, -v165, v125, v124
	v_cmp_ge_f32_e64 s[0:1], 0, v166
	s_nop 1
	v_cndmask_b32_e64 v125, v125, v160, s[0:1]
	v_cmp_lt_f32_e64 s[0:1], 0, v167
	v_max_f32_e32 v84, 0, v84
	s_nop 0
	v_cndmask_b32_e64 v125, v125, v165, s[0:1]
	v_mul_f32_e32 v160, 0x37800000, v125
	v_cndmask_b32_e32 v125, v125, v160, vcc
	v_cmp_class_f32_e32 vcc, v124, v231
	v_max_f32_e32 v90, 0, v90
	v_max_f32_e32 v91, 0, v91
	v_cndmask_b32_e32 v160, v125, v124, vcc
	v_div_scale_f32 v165, s[0:1], v160, v160, 1.0
	v_rcp_f32_e32 v166, v165
	v_div_scale_f32 v167, vcc, 1.0, v160, 1.0
	v_lshl_add_u64 v[124:125], v[142:143], 1, v[120:121]
	v_fma_f32 v168, -v165, v166, 1.0
	v_fmac_f32_e32 v166, v168, v166
	v_mul_f32_e32 v168, v167, v166
	v_fma_f32 v169, -v165, v168, v167
	v_fmac_f32_e32 v168, v169, v166
	v_fma_f32 v165, -v165, v168, v167
	v_div_fmas_f32 v165, v165, v166, v168
	v_div_fixup_f32 v160, v165, v160, 1.0
	v_pk_mul_f32 v[132:133], v[132:133], v[160:161] op_sel_hi:[1,0]
	v_pk_mul_f32 v[128:129], v[128:129], v[160:161] op_sel_hi:[1,0]
	v_pk_mul_f32 v[134:135], v[134:135], v[160:161] op_sel_hi:[1,0]
	v_mul_f32_e32 v161, v161, v160
	v_pk_mul_f32 v[162:163], v[162:163], v[160:161] op_sel_hi:[1,0]
	v_mul_f32_e32 v164, v164, v160
	v_mul_f32_e32 v126, v126, v160
	v_mul_f32_e32 v165, v127, v160
	v_mul_f32_e32 v127, v132, v132
	v_pk_mul_f32 v[130:131], v[130:131], v[160:161] op_sel_hi:[1,0]
	v_mul_f32_e32 v122, v122, v160
	v_mul_f32_e32 v132, v133, v133
	v_pk_mul_f32 v[128:129], v[128:129], v[128:129]
	v_mul_f32_e32 v133, v134, v134
	v_mul_f32_e32 v134, v135, v135
	v_mul_f32_e32 v135, v161, v161
	v_mul_f32_e32 v161, v162, v162
	v_mul_f32_e32 v162, v163, v163
	v_mul_f32_e32 v163, v164, v164
	v_mul_f32_e32 v164, v126, v126
	v_cvt_pk_bf16_f32 v126, v127, v132
	v_cvt_pk_bf16_f32 v127, v133, v134
	v_pk_mul_f32 v[130:131], v[130:131], v[130:131]
	v_cvt_pk_bf16_f32 v128, v128, v129
	v_cvt_pk_bf16_f32 v129, v130, v131
	global_store_dwordx4 v[124:125], v[126:129], off
	v_mul_f32_e32 v123, v123, v160
	s_mov_b32 s0, 0x11000
	v_mul_f32_e32 v127, v165, v165
	v_pk_mul_f32 v[122:123], v[122:123], v[122:123]
	v_cvt_pk_bf16_f32 v126, v135, v162
	v_cvt_pk_bf16_f32 v127, v164, v127
	v_cvt_pk_bf16_f32 v128, v161, v163
	v_cvt_pk_bf16_f32 v129, v122, v123
	v_add_co_u32_e32 v122, vcc, s0, v124
	v_max_f32_e32 v92, 0, v92
	s_nop 0
	v_addc_co_u32_e32 v123, vcc, 0, v125, vcc
	global_store_dwordx4 v[122:123], v[126:129], off offset:-4096
	global_load_dword v126, v[156:157], off offset:64 sc1
	v_max_f32_e32 v93, 0, v93
	v_max_f32_e32 v127, 0, v106
	v_max_f32_e32 v128, 0, v107
	v_max_f32_e32 v86, 0, v86
	v_max_f32_e32 v87, 0, v87
	v_max_f32_e32 v89, 0, v89
	v_max_f32_e32 v88, 0, v88
	v_max_f32_e32 v78, 0, v78
	v_max_f32_e32 v74, 0, v74
	v_max_f32_e32 v79, 0, v79
	v_max_f32_e32 v75, 0, v75
	v_max_f32_e32 v80, 0, v80
	v_max_f32_e32 v76, 0, v76
	v_max_f32_e32 v81, 0, v81
	v_max_f32_e32 v77, 0, v77
	v_max_f32_e32 v66, 0, v66
	v_max_f32_e32 v67, 0, v67
	v_max_f32_e32 v68, 0, v68
	v_max_f32_e32 v69, 0, v69
	v_max_f32_e32 v70, 0, v70
	v_max_f32_e32 v71, 0, v71
	v_max_f32_e32 v72, 0, v72
	v_max_f32_e32 v73, 0, v73
	v_max_f32_e32 v62, 0, v62
	v_max_f32_e32 v58, 0, v58
	v_max_f32_e32 v63, 0, v63
	v_max_f32_e32 v59, 0, v59
	v_max_f32_e32 v64, 0, v64
	v_max_f32_e32 v60, 0, v60
	v_max_f32_e32 v65, 0, v65
	v_max_f32_e32 v61, 0, v61
	v_max_f32_e32 v50, 0, v50
	v_max_f32_e32 v51, 0, v51
	v_max_f32_e32 v52, 0, v52
	v_max_f32_e32 v53, 0, v53
	v_max_f32_e32 v56, 0, v56
	v_max_f32_e32 v57, 0, v57
	s_waitcnt vmcnt(0)
	v_fmamk_f32 v106, v126, 0x39800000, v230
	v_mul_f32_e32 v107, 0x4f800000, v106
	v_cmp_gt_f32_e32 vcc, s28, v106
	v_max_f32_e32 v126, 0, v105
	s_nop 0
	v_cndmask_b32_e32 v106, v106, v107, vcc
	v_sqrt_f32_e32 v107, v106
	s_nop 0
	v_add_u32_e32 v105, -1, v107
	v_add_u32_e32 v129, 1, v107
	v_fma_f32 v130, -v105, v107, v106
	v_fma_f32 v131, -v129, v107, v106
	v_cmp_ge_f32_e64 s[0:1], 0, v130
	s_nop 1
	v_cndmask_b32_e64 v105, v107, v105, s[0:1]
	v_cmp_lt_f32_e64 s[0:1], 0, v131
	s_nop 1
	v_cndmask_b32_e64 v105, v105, v129, s[0:1]
	v_mul_f32_e32 v107, 0x37800000, v105
	v_cndmask_b32_e32 v105, v105, v107, vcc
	v_cmp_class_f32_e32 vcc, v106, v231
	v_max_f32_e32 v46, 0, v46
	v_max_f32_e32 v42, 0, v42
	v_cndmask_b32_e32 v105, v105, v106, vcc
	v_div_scale_f32 v129, s[0:1], v105, v105, 1.0
	v_rcp_f32_e32 v130, v129
	v_add_co_u32_e32 v106, vcc, s80, v124
	v_max_f32_e32 v47, 0, v47
	s_nop 0
	v_addc_co_u32_e32 v107, vcc, 0, v125, vcc
	v_fma_f32 v132, -v129, v130, 1.0
	v_div_scale_f32 v131, vcc, 1.0, v105, 1.0
	v_fmac_f32_e32 v130, v132, v130
	v_mul_f32_e32 v132, v131, v130
	v_fma_f32 v133, -v129, v132, v131
	v_fmac_f32_e32 v132, v133, v130
	v_fma_f32 v129, -v129, v132, v131
	v_div_fmas_f32 v129, v129, v130, v132
	v_div_fixup_f32 v129, v129, v105, 1.0
	v_mul_f32_e32 v100, v100, v129
	v_mul_f32_e32 v105, v110, v129
	v_pk_mul_f32 v[98:99], v[98:99], v[128:129] op_sel:[0,1] op_sel_hi:[1,1]
	v_mul_f32_e32 v104, v104, v129
	v_mul_f32_e32 v132, v100, v100
	v_mul_f32_e32 v100, v126, v129
	v_mul_f32_e32 v101, v101, v129
	v_mul_f32_e32 v110, v127, v129
	v_mul_f32_e32 v111, v111, v129
	v_mul_f32_e32 v127, v128, v129
	v_pk_mul_f32 v[112:113], v[112:113], v[128:129] op_sel:[0,1] op_sel_hi:[1,1]
	v_pk_mul_f32 v[108:109], v[108:109], v[128:129] op_sel:[0,1] op_sel_hi:[1,1]
	v_pk_mul_f32 v[102:103], v[102:103], v[128:129] op_sel:[0,1] op_sel_hi:[1,1]
	v_mul_f32_e32 v105, v105, v105
	v_mul_f32_e32 v130, v98, v98
	v_mul_f32_e32 v98, v103, v103
	v_mul_f32_e32 v131, v99, v99
	v_mul_f32_e32 v99, v104, v104
	v_pk_mul_f32 v[100:101], v[100:101], v[100:101]
	v_pk_mul_f32 v[110:111], v[110:111], v[110:111]
	v_mul_f32_e32 v127, v127, v127
	v_pk_mul_f32 v[112:113], v[112:113], v[112:113]
	v_pk_mul_f32 v[108:109], v[108:109], v[108:109]
	v_mul_f32_e32 v128, v102, v102
	v_cvt_pk_bf16_f32 v102, v105, v111
	v_cvt_pk_bf16_f32 v103, v112, v113
	v_cvt_pk_bf16_f32 v104, v110, v127
	v_cvt_pk_bf16_f32 v105, v108, v109
	global_store_dwordx4 v[124:125], v[102:105], off offset:2048
	v_cvt_pk_bf16_f32 v98, v128, v98
	v_cvt_pk_bf16_f32 v99, v99, v100
	v_cvt_pk_bf16_f32 v100, v130, v131
	v_cvt_pk_bf16_f32 v101, v132, v101
	global_store_dwordx4 v[106:107], v[98:101], off offset:2048
	global_load_dword v98, v[156:157], off offset:128 sc1
	v_max_f32_e32 v43, 0, v43
	v_max_f32_e32 v99, v85, v85
	v_max_f32_e32 v85, 0, v94
	v_max_f32_e32 v94, 0, v95
	v_max_f32_e32 v95, 0, v96
	v_max_f32_e32 v96, 0, v97
	v_max_f32_e32 v97, 0, v82
	v_max_f32_e32 v100, 0, v83
	v_max_f32_e32 v48, 0, v48
	v_max_f32_e32 v44, 0, v44
	v_max_f32_e32 v49, 0, v49
	v_max_f32_e32 v45, 0, v45
	v_max_f32_e32 v34, 0, v34
	v_max_f32_e32 v35, 0, v35
	v_max_f32_e32 v36, 0, v36
	v_max_f32_e32 v37, 0, v37
	v_max_f32_e32 v30, 0, v30
	v_max_f32_e32 v26, 0, v26
	v_max_f32_e32 v31, 0, v31
	v_max_f32_e32 v27, 0, v27
	v_max_f32_e32 v32, 0, v32
	v_max_f32_e32 v28, 0, v28
	v_max_f32_e32 v33, 0, v33
	v_max_f32_e32 v29, 0, v29
	v_max_f32_e32 v18, 0, v18
	v_max_f32_e32 v19, 0, v19
	v_max_f32_e32 v20, 0, v20
	v_max_f32_e32 v21, 0, v21
	v_max_f32_e32 v14, 0, v14
	v_max_f32_e32 v10, 0, v10
	v_max_f32_e32 v15, 0, v15
	v_max_f32_e32 v11, 0, v11
	v_max_f32_e32 v16, 0, v16
	v_max_f32_e32 v12, 0, v12
	v_max_f32_e32 v17, 0, v17
	v_max_f32_e32 v13, 0, v13
	v_max_f32_e32 v2, 0, v2
	v_max_f32_e32 v3, 0, v3
	v_max_f32_e32 v4, 0, v4
	v_max_f32_e32 v5, 0, v5
	s_waitcnt vmcnt(0)
	v_fmamk_f32 v82, v98, 0x39800000, v230
	v_mul_f32_e32 v83, 0x4f800000, v82
	v_cmp_gt_f32_e32 vcc, s28, v82
	s_nop 1
	v_cndmask_b32_e32 v82, v82, v83, vcc
	v_sqrt_f32_e32 v83, v82
	s_nop 0
	v_add_u32_e32 v98, -1, v83
	v_add_u32_e32 v101, 1, v83
	v_fma_f32 v102, -v98, v83, v82
	v_fma_f32 v103, -v101, v83, v82
	v_cmp_ge_f32_e64 s[0:1], 0, v102
	s_nop 1
	v_cndmask_b32_e64 v83, v83, v98, s[0:1]
	v_cmp_lt_f32_e64 s[0:1], 0, v103
	s_nop 1
	v_cndmask_b32_e64 v83, v83, v101, s[0:1]
	v_mul_f32_e32 v98, 0x37800000, v83
	v_cndmask_b32_e32 v83, v83, v98, vcc
	v_cmp_class_f32_e32 vcc, v82, v231
	s_nop 1
	v_cndmask_b32_e32 v98, v83, v82, vcc
	v_div_scale_f32 v101, s[0:1], v98, v98, 1.0
	v_rcp_f32_e32 v102, v101
	v_add_co_u32_e32 v82, vcc, s29, v124
	v_fma_f32 v104, -v101, v102, 1.0
	s_nop 0
	v_addc_co_u32_e32 v83, vcc, 0, v125, vcc
	v_div_scale_f32 v103, vcc, 1.0, v98, 1.0
	v_fmac_f32_e32 v102, v104, v102
	v_mul_f32_e32 v104, v103, v102
	v_fma_f32 v105, -v101, v104, v103
	v_fmac_f32_e32 v104, v105, v102
	v_fma_f32 v101, -v101, v104, v103
	v_div_fmas_f32 v101, v101, v102, v104
	v_div_fixup_f32 v98, v101, v98, 1.0
	v_pk_mul_f32 v[84:85], v[84:85], v[98:99] op_sel_hi:[1,0]
	v_pk_mul_f32 v[90:91], v[90:91], v[98:99] op_sel_hi:[1,0]
	v_pk_mul_f32 v[94:95], v[94:95], v[98:99] op_sel_hi:[1,0]
	v_mul_f32_e32 v96, v96, v98
	v_pk_mul_f32 v[92:93], v[92:93], v[98:99] op_sel_hi:[1,0]
	v_pk_mul_f32 v[86:87], v[86:87], v[98:99] op_sel_hi:[1,0]
	v_mul_f32_e32 v85, v85, v85
	v_mul_f32_e32 v94, v94, v94
	v_mul_f32_e32 v103, v84, v84
	v_cvt_pk_bf16_f32 v84, v85, v94
	v_pk_mul_f32 v[90:91], v[90:91], v[90:91]
	v_mul_f32_e32 v95, v95, v95
	v_mul_f32_e32 v96, v96, v96
	v_pk_mul_f32 v[92:93], v[92:93], v[92:93]
	v_mul_f32_e32 v101, v86, v86
	v_mul_f32_e32 v102, v87, v87
	v_cvt_pk_bf16_f32 v85, v95, v96
	v_cvt_pk_bf16_f32 v86, v90, v91
	v_cvt_pk_bf16_f32 v87, v92, v93
	global_store_dwordx4 v[82:83], v[84:87], off
	v_mul_f32_e32 v97, v97, v98
	s_nop 0
	v_max_f32_e32 v84, 0, v99
	v_mul_f32_e32 v84, v84, v98
	v_mul_f32_e32 v100, v100, v98
	v_pk_mul_f32 v[88:89], v[88:89], v[98:99] op_sel_hi:[1,0]
	v_mul_f32_e32 v85, v89, v89
	v_mul_f32_e32 v87, v84, v84
	v_mul_f32_e32 v97, v97, v97
	v_mul_f32_e32 v100, v100, v100
	v_mul_f32_e32 v88, v88, v88
	v_cvt_pk_bf16_f32 v84, v101, v102
	v_cvt_pk_bf16_f32 v85, v88, v85
	v_cvt_pk_bf16_f32 v86, v97, v100
	v_cvt_pk_bf16_f32 v87, v103, v87
	global_store_dwordx4 v[122:123], v[84:87], off
	global_load_dword v84, v[156:157], off offset:192 sc1
	s_waitcnt vmcnt(0)
	v_fmamk_f32 v84, v84, 0x39800000, v230
	v_mul_f32_e32 v85, 0x4f800000, v84
	v_cmp_gt_f32_e32 vcc, s28, v84
	s_nop 1
	v_cndmask_b32_e32 v84, v84, v85, vcc
	v_sqrt_f32_e32 v85, v84
	s_nop 0
	v_add_u32_e32 v86, -1, v85
	v_add_u32_e32 v87, 1, v85
	v_fma_f32 v88, -v86, v85, v84
	v_fma_f32 v89, -v87, v85, v84
	v_cmp_ge_f32_e64 s[0:1], 0, v88
	s_nop 1
	v_cndmask_b32_e64 v85, v85, v86, s[0:1]
	v_cmp_lt_f32_e64 s[0:1], 0, v89
	s_nop 1
	v_cndmask_b32_e64 v85, v85, v87, s[0:1]
	v_mul_f32_e32 v86, 0x37800000, v85
	v_cndmask_b32_e32 v85, v85, v86, vcc
	v_cmp_class_f32_e32 vcc, v84, v231
	s_nop 1
	v_cndmask_b32_e32 v84, v85, v84, vcc
	v_div_scale_f32 v85, s[0:1], v84, v84, 1.0
	v_rcp_f32_e32 v86, v85
	v_div_scale_f32 v87, vcc, 1.0, v84, 1.0
	v_fma_f32 v88, -v85, v86, 1.0
	v_fmac_f32_e32 v86, v88, v86
	v_mul_f32_e32 v88, v87, v86
	v_fma_f32 v89, -v85, v88, v87
	v_fmac_f32_e32 v88, v89, v86
	v_fma_f32 v85, -v85, v88, v87
	v_div_fmas_f32 v85, v85, v86, v88
	v_div_fixup_f32 v84, v85, v84, 1.0
	v_pk_mul_f32 v[78:79], v[78:79], v[84:85] op_sel_hi:[1,0]
	v_pk_mul_f32 v[74:75], v[74:75], v[84:85] op_sel_hi:[1,0]
	v_pk_mul_f32 v[80:81], v[80:81], v[84:85] op_sel_hi:[1,0]
	v_pk_mul_f32 v[76:77], v[76:77], v[84:85] op_sel_hi:[1,0]
	v_pk_mul_f32 v[66:67], v[66:67], v[84:85] op_sel_hi:[1,0]
	v_pk_mul_f32 v[68:69], v[68:69], v[84:85] op_sel_hi:[1,0]
	v_pk_mul_f32 v[70:71], v[70:71], v[84:85] op_sel_hi:[1,0]
	v_pk_mul_f32 v[72:73], v[72:73], v[84:85] op_sel_hi:[1,0]
	v_pk_mul_f32 v[78:79], v[78:79], v[78:79]
	v_pk_mul_f32 v[74:75], v[74:75], v[74:75]
	v_pk_mul_f32 v[80:81], v[80:81], v[80:81]
	v_pk_mul_f32 v[76:77], v[76:77], v[76:77]
	v_pk_mul_f32 v[84:85], v[66:67], v[66:67]
	v_pk_mul_f32 v[86:87], v[68:69], v[68:69]
	v_cvt_pk_bf16_f32 v66, v78, v79
	v_cvt_pk_bf16_f32 v67, v80, v81
	v_cvt_pk_bf16_f32 v68, v74, v75
	v_cvt_pk_bf16_f32 v69, v76, v77
	v_pk_mul_f32 v[70:71], v[70:71], v[70:71]
	v_pk_mul_f32 v[72:73], v[72:73], v[72:73]
	global_store_dwordx4 v[82:83], v[66:69], off offset:2048
	s_nop 1
	v_cvt_pk_bf16_f32 v66, v70, v71
	v_cvt_pk_bf16_f32 v67, v72, v73
	v_cvt_pk_bf16_f32 v68, v84, v85
	v_cvt_pk_bf16_f32 v69, v86, v87
	global_store_dwordx4 v[122:123], v[66:69], off offset:2048
	global_load_dword v66, v[156:157], off offset:512 sc1
	s_nop 0
	v_max_f32_e32 v67, 0, v54
	v_max_f32_e32 v68, 0, v55
	s_waitcnt vmcnt(0)
	v_fmamk_f32 v54, v66, 0x39800000, v230
	v_mul_f32_e32 v55, 0x4f800000, v54
	v_cmp_gt_f32_e32 vcc, s28, v54
	s_nop 1
	v_cndmask_b32_e32 v54, v54, v55, vcc
	v_sqrt_f32_e32 v55, v54
	s_nop 0
	v_add_u32_e32 v66, -1, v55
	v_add_u32_e32 v69, 1, v55
	v_fma_f32 v70, -v66, v55, v54
	v_fma_f32 v71, -v69, v55, v54
	v_cmp_ge_f32_e64 s[0:1], 0, v70
	s_nop 1
	v_cndmask_b32_e64 v55, v55, v66, s[0:1]
	v_cmp_lt_f32_e64 s[0:1], 0, v71
	s_nop 1
	v_cndmask_b32_e64 v55, v55, v69, s[0:1]
	v_mul_f32_e32 v66, 0x37800000, v55
	v_cndmask_b32_e32 v55, v55, v66, vcc
	v_cmp_class_f32_e32 vcc, v54, v231
	s_nop 1
	v_cndmask_b32_e32 v66, v55, v54, vcc
	v_div_scale_f32 v69, s[0:1], v66, v66, 1.0
	v_rcp_f32_e32 v70, v69
	v_div_scale_f32 v71, vcc, 1.0, v66, 1.0
	v_lshl_add_u64 v[54:55], v[144:145], 1, v[120:121]
	v_fma_f32 v72, -v69, v70, 1.0
	v_fmac_f32_e32 v70, v72, v70
	v_mul_f32_e32 v72, v71, v70
	v_fma_f32 v73, -v69, v72, v71
	v_fmac_f32_e32 v72, v73, v70
	v_fma_f32 v69, -v69, v72, v71
	v_div_fmas_f32 v69, v69, v70, v72
	v_div_fixup_f32 v66, v69, v66, 1.0
	v_pk_mul_f32 v[62:63], v[62:63], v[66:67] op_sel_hi:[1,0]
	v_pk_mul_f32 v[58:59], v[58:59], v[66:67] op_sel_hi:[1,0]
	v_pk_mul_f32 v[64:65], v[64:65], v[66:67] op_sel_hi:[1,0]
	v_pk_mul_f32 v[60:61], v[60:61], v[66:67] op_sel_hi:[1,0]
	v_mul_f32_e32 v67, v67, v66
	v_pk_mul_f32 v[50:51], v[50:51], v[66:67] op_sel_hi:[1,0]
	v_pk_mul_f32 v[52:53], v[52:53], v[66:67] op_sel_hi:[1,0]
	v_mul_f32_e32 v68, v68, v66
	v_pk_mul_f32 v[56:57], v[56:57], v[66:67] op_sel_hi:[1,0]
	v_pk_mul_f32 v[62:63], v[62:63], v[62:63]
	v_pk_mul_f32 v[58:59], v[58:59], v[58:59]
	v_pk_mul_f32 v[64:65], v[64:65], v[64:65]
	v_pk_mul_f32 v[60:61], v[60:61], v[60:61]
	v_mul_f32_e32 v66, v67, v67
	v_mul_f32_e32 v67, v50, v50
	v_mul_f32_e32 v69, v51, v51
	v_pk_mul_f32 v[70:71], v[52:53], v[52:53]
	v_cvt_pk_bf16_f32 v50, v62, v63
	v_cvt_pk_bf16_f32 v51, v64, v65
	v_cvt_pk_bf16_f32 v52, v58, v59
	v_cvt_pk_bf16_f32 v53, v60, v61
	global_store_dwordx4 v[54:55], v[50:53], off
	v_add_co_u32_e32 v54, vcc, s80, v54
	v_mul_f32_e32 v68, v68, v68
	s_nop 0
	v_addc_co_u32_e32 v55, vcc, 0, v55, vcc
	v_pk_mul_f32 v[56:57], v[56:57], v[56:57]
	v_cvt_pk_bf16_f32 v50, v66, v68
	v_cvt_pk_bf16_f32 v51, v56, v57
	v_cvt_pk_bf16_f32 v52, v67, v69
	v_cvt_pk_bf16_f32 v53, v70, v71
	global_store_dwordx4 v[54:55], v[50:53], off
	global_load_dword v50, v[156:157], off offset:576 sc1
	v_max_f32_e32 v54, 0, v41
	v_max_f32_e32 v51, 0, v38
	v_max_f32_e32 v52, 0, v39
	v_max_f32_e32 v53, 0, v40
	s_waitcnt vmcnt(0)
	v_fmamk_f32 v38, v50, 0x39800000, v230
	v_mul_f32_e32 v39, 0x4f800000, v38
	v_cmp_gt_f32_e32 vcc, s28, v38
	s_nop 1
	v_cndmask_b32_e32 v40, v38, v39, vcc
	v_sqrt_f32_e32 v50, v40
	v_lshl_add_u64 v[38:39], v[146:147], 1, v[120:121]
	v_add_u32_e32 v41, -1, v50
	v_add_u32_e32 v55, 1, v50
	v_fma_f32 v56, -v41, v50, v40
	v_fma_f32 v57, -v55, v50, v40
	v_cmp_ge_f32_e64 s[0:1], 0, v56
	s_nop 1
	v_cndmask_b32_e64 v41, v50, v41, s[0:1]
	v_cmp_lt_f32_e64 s[0:1], 0, v57
	s_nop 1
	v_cndmask_b32_e64 v41, v41, v55, s[0:1]
	v_mul_f32_e32 v50, 0x37800000, v41
	v_cndmask_b32_e32 v41, v41, v50, vcc
	v_cmp_class_f32_e32 vcc, v40, v231
	s_nop 1
	v_cndmask_b32_e32 v50, v41, v40, vcc
	v_div_scale_f32 v55, s[0:1], v50, v50, 1.0
	v_rcp_f32_e32 v56, v55
	v_add_co_u32_e32 v40, vcc, s80, v38
	v_fma_f32 v58, -v55, v56, 1.0
	s_nop 0
	v_addc_co_u32_e32 v41, vcc, 0, v39, vcc
	v_div_scale_f32 v57, vcc, 1.0, v50, 1.0
	v_fmac_f32_e32 v56, v58, v56
	v_mul_f32_e32 v58, v57, v56
	v_fma_f32 v59, -v55, v58, v57
	v_fmac_f32_e32 v58, v59, v56
	v_fma_f32 v55, -v55, v58, v57
	v_div_fmas_f32 v55, v55, v56, v58
	v_div_fixup_f32 v50, v55, v50, 1.0
	v_pk_mul_f32 v[46:47], v[46:47], v[50:51] op_sel_hi:[1,0]
	v_pk_mul_f32 v[42:43], v[42:43], v[50:51] op_sel_hi:[1,0]
	v_pk_mul_f32 v[48:49], v[48:49], v[50:51] op_sel_hi:[1,0]
	v_pk_mul_f32 v[44:45], v[44:45], v[50:51] op_sel_hi:[1,0]
	v_mul_f32_e32 v51, v51, v50
	v_pk_mul_f32 v[34:35], v[34:35], v[50:51] op_sel_hi:[1,0]
	v_pk_mul_f32 v[36:37], v[36:37], v[50:51] op_sel_hi:[1,0]
	v_pk_mul_f32 v[52:53], v[52:53], v[50:51] op_sel_hi:[1,0]
	v_mul_f32_e32 v54, v54, v50
	v_pk_mul_f32 v[46:47], v[46:47], v[46:47]
	v_pk_mul_f32 v[42:43], v[42:43], v[42:43]
	v_pk_mul_f32 v[48:49], v[48:49], v[48:49]
	v_pk_mul_f32 v[44:45], v[44:45], v[44:45]
	v_mul_f32_e32 v50, v51, v51
	v_mul_f32_e32 v51, v34, v34
	v_mul_f32_e32 v55, v35, v35
	v_pk_mul_f32 v[56:57], v[36:37], v[36:37]
	v_cvt_pk_bf16_f32 v34, v46, v47
	v_cvt_pk_bf16_f32 v35, v48, v49
	v_cvt_pk_bf16_f32 v36, v42, v43
	v_cvt_pk_bf16_f32 v37, v44, v45
	v_pk_mul_f32 v[52:53], v[52:53], v[52:53]
	v_mul_f32_e32 v54, v54, v54
	global_store_dwordx4 v[38:39], v[34:37], off
	v_max_f32_e32 v38, 0, v25
	s_nop 0
	v_cvt_pk_bf16_f32 v34, v50, v52
	v_cvt_pk_bf16_f32 v35, v53, v54
	v_cvt_pk_bf16_f32 v36, v51, v55
	v_cvt_pk_bf16_f32 v37, v56, v57
	global_store_dwordx4 v[40:41], v[34:37], off
	global_load_dword v34, v[156:157], off offset:640 sc1
	s_nop 0
	v_max_f32_e32 v35, 0, v22
	v_max_f32_e32 v36, 0, v23
	v_max_f32_e32 v37, 0, v24
	s_waitcnt vmcnt(0)
	v_fmamk_f32 v22, v34, 0x39800000, v230
	v_mul_f32_e32 v23, 0x4f800000, v22
	v_cmp_gt_f32_e32 vcc, s28, v22
	s_nop 1
	v_cndmask_b32_e32 v24, v22, v23, vcc
	v_sqrt_f32_e32 v34, v24
	v_lshl_add_u64 v[22:23], v[148:149], 1, v[120:121]
	v_add_u32_e32 v25, -1, v34
	v_add_u32_e32 v39, 1, v34
	v_fma_f32 v40, -v25, v34, v24
	v_fma_f32 v41, -v39, v34, v24
	v_cmp_ge_f32_e64 s[0:1], 0, v40
	s_nop 1
	v_cndmask_b32_e64 v25, v34, v25, s[0:1]
	v_cmp_lt_f32_e64 s[0:1], 0, v41
	s_nop 1
	v_cndmask_b32_e64 v25, v25, v39, s[0:1]
	v_mul_f32_e32 v34, 0x37800000, v25
	v_cndmask_b32_e32 v25, v25, v34, vcc
	v_cmp_class_f32_e32 vcc, v24, v231
	s_nop 1
	v_cndmask_b32_e32 v34, v25, v24, vcc
	v_div_scale_f32 v39, s[0:1], v34, v34, 1.0
	v_rcp_f32_e32 v40, v39
	v_add_co_u32_e32 v24, vcc, s80, v22
	v_fma_f32 v42, -v39, v40, 1.0
	s_nop 0
	v_addc_co_u32_e32 v25, vcc, 0, v23, vcc
	v_div_scale_f32 v41, vcc, 1.0, v34, 1.0
	v_fmac_f32_e32 v40, v42, v40
	v_mul_f32_e32 v42, v41, v40
	v_fma_f32 v43, -v39, v42, v41
	v_fmac_f32_e32 v42, v43, v40
	v_fma_f32 v39, -v39, v42, v41
	v_div_fmas_f32 v39, v39, v40, v42
	v_div_fixup_f32 v34, v39, v34, 1.0
	v_pk_mul_f32 v[30:31], v[30:31], v[34:35] op_sel_hi:[1,0]
	v_pk_mul_f32 v[26:27], v[26:27], v[34:35] op_sel_hi:[1,0]
	v_pk_mul_f32 v[32:33], v[32:33], v[34:35] op_sel_hi:[1,0]
	v_pk_mul_f32 v[28:29], v[28:29], v[34:35] op_sel_hi:[1,0]
	v_mul_f32_e32 v35, v35, v34
	v_pk_mul_f32 v[18:19], v[18:19], v[34:35] op_sel_hi:[1,0]
	v_pk_mul_f32 v[20:21], v[20:21], v[34:35] op_sel_hi:[1,0]
	v_pk_mul_f32 v[36:37], v[36:37], v[34:35] op_sel_hi:[1,0]
	v_mul_f32_e32 v38, v38, v34
	v_pk_mul_f32 v[30:31], v[30:31], v[30:31]
	v_pk_mul_f32 v[26:27], v[26:27], v[26:27]
	v_pk_mul_f32 v[32:33], v[32:33], v[32:33]
	v_pk_mul_f32 v[28:29], v[28:29], v[28:29]
	v_mul_f32_e32 v34, v35, v35
	v_mul_f32_e32 v35, v18, v18
	v_mul_f32_e32 v39, v19, v19
	v_pk_mul_f32 v[40:41], v[20:21], v[20:21]
	v_cvt_pk_bf16_f32 v18, v30, v31
	v_cvt_pk_bf16_f32 v19, v32, v33
	v_cvt_pk_bf16_f32 v20, v26, v27
	v_cvt_pk_bf16_f32 v21, v28, v29
	v_pk_mul_f32 v[36:37], v[36:37], v[36:37]
	v_mul_f32_e32 v38, v38, v38
	global_store_dwordx4 v[22:23], v[18:21], off
	s_nop 1
	v_cvt_pk_bf16_f32 v18, v34, v36
	v_cvt_pk_bf16_f32 v19, v37, v38
	v_cvt_pk_bf16_f32 v20, v35, v39
	v_cvt_pk_bf16_f32 v21, v40, v41
	global_store_dwordx4 v[24:25], v[18:21], off
	global_load_dword v18, v[156:157], off offset:704 sc1
	s_nop 0
	v_max_f32_e32 v19, 0, v6
	v_max_f32_e32 v20, 0, v7
	v_max_f32_e32 v21, 0, v8
	s_waitcnt vmcnt(0)
	v_fmamk_f32 v6, v18, 0x39800000, v230
	v_mul_f32_e32 v7, 0x4f800000, v6
	v_cmp_gt_f32_e32 vcc, s28, v6
	v_max_f32_e32 v18, 0, v9
	s_nop 0
	v_cndmask_b32_e32 v6, v6, v7, vcc
	v_sqrt_f32_e32 v7, v6
	s_nop 0
	v_add_u32_e32 v8, -1, v7
	v_add_u32_e32 v9, 1, v7
	v_fma_f32 v22, -v8, v7, v6
	v_fma_f32 v23, -v9, v7, v6
	v_cmp_ge_f32_e64 s[0:1], 0, v22
	s_nop 1
	v_cndmask_b32_e64 v7, v7, v8, s[0:1]
	v_cmp_lt_f32_e64 s[0:1], 0, v23
	s_nop 1
	v_cndmask_b32_e64 v7, v7, v9, s[0:1]
	v_mul_f32_e32 v8, 0x37800000, v7
	v_cndmask_b32_e32 v7, v7, v8, vcc
	v_cmp_class_f32_e32 vcc, v6, v231
	s_nop 1
	v_cndmask_b32_e32 v9, v7, v6, vcc
	v_div_scale_f32 v8, s[0:1], v9, v9, 1.0
	v_rcp_f32_e32 v22, v8
	v_div_scale_f32 v23, vcc, 1.0, v9, 1.0
	v_lshl_add_u64 v[6:7], v[150:151], 1, v[120:121]
	v_fma_f32 v24, -v8, v22, 1.0
	v_fmac_f32_e32 v22, v24, v22
	v_mul_f32_e32 v24, v23, v22
	v_fma_f32 v25, -v8, v24, v23
	v_fmac_f32_e32 v24, v25, v22
	v_fma_f32 v8, -v8, v24, v23
	v_div_fmas_f32 v22, v8, v22, v24
	v_add_co_u32_e32 v8, vcc, 0x10000, v6
	v_div_fixup_f32 v22, v22, v9, 1.0
	s_nop 0
	v_addc_co_u32_e32 v9, vcc, 0, v7, vcc
	v_pk_mul_f32 v[14:15], v[14:15], v[22:23] op_sel_hi:[1,0]
	v_pk_mul_f32 v[10:11], v[10:11], v[22:23] op_sel_hi:[1,0]
	v_pk_mul_f32 v[16:17], v[16:17], v[22:23] op_sel_hi:[1,0]
	v_pk_mul_f32 v[12:13], v[12:13], v[22:23] op_sel_hi:[1,0]
	v_pk_mul_f32 v[2:3], v[2:3], v[22:23] op_sel_hi:[1,0]
	v_pk_mul_f32 v[4:5], v[4:5], v[22:23] op_sel_hi:[1,0]
	v_pk_mul_f32 v[20:21], v[20:21], v[22:23] op_sel_hi:[1,0]
	v_pk_mul_f32 v[18:19], v[18:19], v[22:23] op_sel_hi:[1,0]
	v_pk_mul_f32 v[14:15], v[14:15], v[14:15]
	v_pk_mul_f32 v[10:11], v[10:11], v[10:11]
	v_pk_mul_f32 v[16:17], v[16:17], v[16:17]
	v_pk_mul_f32 v[12:13], v[12:13], v[12:13]
	v_pk_mul_f32 v[22:23], v[2:3], v[2:3]
	v_pk_mul_f32 v[24:25], v[4:5], v[4:5]
	v_cvt_pk_bf16_f32 v2, v14, v15
	v_cvt_pk_bf16_f32 v3, v16, v17
	v_cvt_pk_bf16_f32 v4, v10, v11
	v_cvt_pk_bf16_f32 v5, v12, v13
	s_andn2_b64 vcc, exec, s[44:45]
	s_mov_b64 s[0:1], -1
	v_pk_mul_f32 v[20:21], v[20:21], v[20:21]
	v_pk_mul_f32 v[18:19], v[18:19], v[18:19]
	global_store_dwordx4 v[6:7], v[2:5], off
	s_nop 1
	v_cvt_pk_bf16_f32 v2, v19, v20
	v_cvt_pk_bf16_f32 v3, v21, v18
	v_cvt_pk_bf16_f32 v4, v22, v23
	v_cvt_pk_bf16_f32 v5, v24, v25
	global_store_dwordx4 v[8:9], v[2:5], off
	s_cbranch_vccnz .LBB0_1153
	s_andn2_b64 vcc, exec, s[24:25]
	s_cbranch_vccnz .LBB0_1152
	s_barrier
	s_branch .LBB0_1152
